# prologue row sum-of-squares: butterfly by DPP + permlane16/32 swaps instead of six serialized ds_bpermute round trips
# baseline (speedup 1.0000x reference)
; __device__ __forceinline__ unsigned cvt_pk_bf16(float lo, float hi) { unsigned r; asm volatile("v_cvt_pk_bf16_f32 %0, %1, %2" : "=v"(r) : "v"(lo), "v"(hi)); return r; }
; __device__ __forceinline__ float sq4(f32x4 a) { return (a[0] * a[0] + a[1] * a[1]) + (a[2] * a[2] + a[3] * a[3]); }
; __device__ __forceinline__ float wave_sum(float v) {
; #pragma unroll
;     for (int o = 1; o < 64; o <<= 1) v += __shfl_xor(v, o);
;     return v;
; __device__ __forceinline__ void prologue(const Args& a, LAS unsigned char* lds, int tid, int lane, int wid) {
;     ...
;       for (int m = gw; m < MTOK; m += NGW) {
;           const float* src = (m < MPROMPT) ? xp + (size_t)m * DM : xs + (size_t)(m - MPROMPT) * DM;
;           f32x4 v[4]; float s = 0.f;
; #pragma unroll
;           for (int j = 0; j < 4; ++j) { v[j] = *(const f32x4*)(src + (lane + 64 * j) * 4); s += sq4(v[j]); }
;           s = wave_sum(s);
; #pragma unroll
;           for (int j = 0; j < 4; ++j) { u32x2 o; o.x = cvt_pk_bf16(v[j][0], v[j][1]); o.y = cvt_pk_bf16(v[j][2], v[j][3]); *(u32x2*)(xb + (size_t)m * DM + (lane + 64 * j) * 4) = o; }
;           if (lane < 16) ss[(size_t)m * 16 + lane] = (lane == 0) ? s : 0.f;
.LBB0_444:
	s_waitcnt lgkmcnt(0)
	global_load_dwordx4 v[12:15], v10, s[80:81]
	global_load_dwordx4 v[16:19], v10, s[80:81] offset:1024
	global_load_dwordx4 v[20:23], v10, s[80:81] offset:2048
	global_load_dwordx4 v[24:27], v10, s[80:81] offset:3072
	s_lshl_b64 s[16:17], s[44:45], 11
	s_waitcnt vmcnt(3)
	v_mul_f32_e32 v11, v13, v13
	v_mul_f32_e32 v28, v15, v15
	s_waitcnt vmcnt(2)
	v_mul_f32_e32 v29, v17, v17
	v_mul_f32_e32 v30, v19, v19
	s_waitcnt vmcnt(1)
	v_mul_f32_e32 v31, v21, v21
	v_mul_f32_e32 v32, v23, v23
	v_fmac_f32_e32 v11, v12, v12
	v_fmac_f32_e32 v28, v14, v14
	v_fmac_f32_e32 v29, v16, v16
	v_fmac_f32_e32 v30, v18, v18
	s_waitcnt vmcnt(0)
	v_mul_f32_e32 v33, v25, v25
	v_mul_f32_e32 v34, v27, v27
	v_fmac_f32_e32 v31, v20, v20
	v_fmac_f32_e32 v32, v22, v22
	v_add_f32_e32 v11, v11, v28
	v_add_f32_e32 v28, v29, v30
	v_fmac_f32_e32 v33, v24, v24
	v_fmac_f32_e32 v34, v26, v26
	v_add_f32_e32 v29, v31, v32
	v_add_f32_e32 v11, v11, v28
	v_add_f32_e32 v30, v33, v34
	v_add_f32_e32 v11, v11, v29
	v_add_f32_e32 v11, v11, v30
	v_cvt_pk_bf16_f32 v12, v12, v13
	v_cvt_pk_bf16_f32 v13, v14, v15
	s_waitcnt lgkmcnt(0)
	s_nop 1
	v_add_f32_dpp v28, v11, v11 quad_perm:[1,0,3,2] row_mask:0xf bank_mask:0xf
	v_mov_b32_e32 v11, v28
	s_waitcnt lgkmcnt(0)
	s_nop 1
	v_add_f32_dpp v28, v11, v11 quad_perm:[2,3,0,1] row_mask:0xf bank_mask:0xf
	v_mov_b32_e32 v11, v28
	s_waitcnt lgkmcnt(0)
	s_nop 1
	v_add_f32_dpp v28, v11, v11 row_half_mirror row_mask:0xf bank_mask:0xf
	v_mov_b32_e32 v11, v28
	v_lshl_add_u64 v[28:29], v[2:3], 0, s[16:17]
	global_store_dwordx2 v[28:29], v[12:13], off
	v_cvt_pk_bf16_f32 v12, v16, v17
	v_cvt_pk_bf16_f32 v13, v18, v19
	s_waitcnt lgkmcnt(0)
	s_nop 1
	v_add_f32_dpp v30, v11, v11 row_mirror row_mask:0xf bank_mask:0xf
	v_mov_b32_e32 v11, v30
	global_store_dwordx2 v[28:29], v[12:13], off offset:512
	v_cvt_pk_bf16_f32 v14, v20, v21
	s_waitcnt lgkmcnt(0)
	v_mov_b32_e32 v15, v11
	s_nop 1
	v_permlane16_swap_b32_e32 v11, v15
	v_add_f32_e32 v11, v11, v15
	v_mov_b32_e32 v12, v11
	s_nop 1
	v_permlane32_swap_b32_e32 v11, v12
	v_cvt_pk_bf16_f32 v15, v22, v23
	global_store_dwordx2 v[28:29], v[14:15], off offset:1024
	v_cvt_pk_bf16_f32 v14, v24, v25
	v_cvt_pk_bf16_f32 v15, v26, v27
	global_store_dwordx2 v[28:29], v[14:15], off offset:1536
	s_and_saveexec_b64 s[80:81], vcc
	s_cbranch_execz .LBB0_441
	s_waitcnt lgkmcnt(0)
	v_add_f32_e32 v11, v11, v12
	s_lshl_b64 s[16:17], s[44:45], 6
	v_cndmask_b32_e64 v11, 0, v11, s[38:39]
	v_lshl_add_u64 v[12:13], v[0:1], 0, s[16:17]
	global_store_dword v[12:13], v11, off
	s_branch .LBB0_441
